# merge phase k-loop: next k-tile issued mid-iteration after a second barrier, two tiles in flight, counted vmcnt, chain issues next op tiles 0 and 1
# baseline (speedup 1.0000x reference)
; #define LAS __attribute__((address_space(3)))
; DI int otid() { int t = threadIdx.x; asm volatile("" : "+v"(t)); return t; }
; DI int vblock() { const int G = gridDim.x; return (G & 7) ? (int)blockIdx.x : (int)((blockIdx.x & 7) * (G >> 3) + (blockIdx.x >> 3)); }
; DI void phase_merge(const Params& p, int l, LAS char* lds) {
;     const int tidx = otid();
;     const bf16_t* h = (const bf16_t*)(p.ws + OFF_H);
;     const bf16_t* u = (const bf16_t*)(p.ws + OFF_U);
;     const bf16_t* W = (const bf16_t*)(p.ws + OFF_W) + (size_t)l * W_LAYER;
;     bf16_t* m = (bf16_t*)(p.ws + OFF_ZM);
;     const float* gb = p.gate_bias + l * 4096;
;     const int lane = tidx & 63, w = tidx >> 6, wm = w >> 1, wn = w & 1, fr = lane & 15, fq = lane >> 4;
;     unsigned* stash = (unsigned*)(p.ws + OFF_ZC) + tidx;
;     const int G = gridDim.x, NT = 257 * 8, vb = vblock();
;     const int ntl = (vb < NT) ? (NT - vb + G - 1) / G : 0;
;     const int nops = 8 * ntl;
;     auto op_of = [&](int f) {
;         if (f < 4 * ntl) {
;             const int br = f / ntl, i = vb + (f - br * ntl) * G, mt = i >> 3, nt = i & 7;
;             return GOp{h + (size_t)mt * 128 * 1024, W + W_IN + (size_t)(3328 + br * 1024 + nt * 128) * 1024, 1024, 1024, 1024, 2 * (mt + nt)};
;         }
;         const int f2 = f - 4 * ntl, k = f2 >> 2, br = f2 & 3, i = vb + k * G, mt = i >> 3, nt = i & 7;
;         const int koff = (br == 0) ? 0 : (br == 1) ? 256 : (br == 2) ? 768 : 1024;
;         const int kk = (br == 1) ? 512 : 256;
;         const size_t woff = (br == 0) ? W_OP : (br == 1) ? W_OM : (br == 2) ? W_OC : W_OS;
;         return GOp{u + (size_t)mt * 128 * 1280 + koff, W + woff + (size_t)nt * 128 * kk, 1280, kk, kk, mt + nt};
;     };
;     f32x4 acc[4][4];
;     bool inflight = false;
;     unsigned sq[4][4], sqn[4][4];
; #pragma unroll
;     for (int mi = 0; mi < 4; ++mi)
; #pragma unroll
;         for (int ni = 0; ni < 4; ++ni) { sq[mi][ni] = 0x01010101u; sqn[mi][ni] = 0x01010101u; }
.LBB0_232:
	s_cmp_lt_i32 s60, 1
	s_cbranch_scc1 .LBB0_278
	v_readlane_b32 s4, v228, 30
	s_lshl_b32 s61, s60, 3
	s_mul_i32 s1, s4, 0x13a0000
	s_mul_hi_i32 s0, s4, 0x13a0000
	s_add_u32 s62, s98, s1
	s_addc_u32 s63, s99, s0
	s_lshl_b32 s0, s4, 12
	s_ashr_i32 s1, s0, 31
	v_readlane_b32 s4, v229, 45
	v_lshrrev_b32_e32 v5, 4, v2
	s_lshl_b64 s[0:1], s[0:1], 2
	v_readlane_b32 s12, v229, 53
	v_xor_b32_e32 v5, v5, v2
	v_readlane_b32 s13, v229, 54
	s_add_u32 s64, s12, s0
	v_lshlrev_b32_e32 v7, 4, v2
	v_lshlrev_b32_e32 v5, 3, v5
	s_addc_u32 s65, s13, s1
	v_readlane_b32 s12, v228, 19
	v_and_b32_e32 v178, 56, v5
	v_add_u32_e32 v5, 0x1000, v7
	v_readlane_b32 s13, v228, 20
	v_ashrrev_i32_e32 v3, 31, v2
	v_ashrrev_i32_e32 v179, 7, v5
	v_add_u32_e32 v5, 0x2000, v7
	v_lshl_add_u64 v[152:153], v[2:3], 2, s[12:13]
	v_lshrrev_b32_e32 v3, 2, v2
	v_ashrrev_i32_e32 v180, 7, v5
	v_add_u32_e32 v5, 0x3000, v7
	v_and_b32_e32 v6, 12, v3
	v_and_b32_e32 v3, 48, v2
	v_ashrrev_i32_e32 v181, 7, v5
	v_lshlrev_b32_e32 v5, 3, v2
	s_movk_i32 s0, 0x70
	v_and_b32_e32 v1, 15, v2
	v_bitop3_b32 v182, v5, s0, v3 bitop3:0x48
	v_ashrrev_i32_e32 v3, 1, v2
	s_movk_i32 s0, 0xffc0
	v_and_or_b32 v183, v3, s0, v1
	v_lshlrev_b32_e32 v1, 7, v2
	v_and_b32_e32 v185, 0x2780, v1
	v_cvt_f32_u32_e32 v1, s60
	v_readlane_b32 s18, v229, 59
	v_readlane_b32 s19, v229, 60
	v_readlane_b32 s18, v228, 17
	v_rcp_iflag_f32_e32 v1, v1
	v_and_b32_e32 v4, 64, v2
	v_readlane_b32 s19, v228, 18
	v_lshlrev_b32_e32 v148, 1, v4
	v_mul_f32_e32 v1, 0x4f7ffffe, v1
	v_cvt_u32_f32_e32 v1, v1
	v_and_b32_e32 v3, 16, v2
	s_sub_i32 s0, 0, s60
	v_readlane_b32 s14, v229, 55
	v_readfirstlane_b32 s1, v1
	v_readlane_b32 s15, v229, 56
	v_readlane_b32 s16, v229, 57
	v_readlane_b32 s17, v229, 58
	v_and_b32_e32 v160, 0xfffffc00, v7
	v_bfe_i32 v161, v2, 3, 25
	v_bitop3_b32 v7, v5, v2, 48 bitop3:0x78
	v_lshl_add_u64 v[8:9], s[18:19], 0, v[148:149]
	v_lshlrev_b32_e32 v148, 1, v3
	v_lshrrev_b32_e32 v2, 1, v2
	s_mul_i32 s0, s0, s1
	v_readlane_b32 s10, v229, 51
	v_readlane_b32 s16, v229, 63
	v_readlane_b32 s14, v229, 61
	v_lshl_add_u64 v[8:9], v[8:9], 0, v[148:149]
	v_and_b32_e32 v148, 16, v2
	s_mul_hi_u32 s0, s1, s0
	s_mov_b32 s10, 0x800000
	v_readlane_b32 s17, v228, 0
	v_readlane_b32 s15, v229, 62
	s_lshl_b32 s66, s60, 2
	v_lshlrev_b32_e32 v184, 7, v183
	v_bitop3_b32 v186, v7, 64, v168 bitop3:0x6c
	v_lshl_add_u64 v[154:155], v[8:9], 0, v[148:149]
	s_max_i32 s67, s61, 1
	s_mov_b32 s33, 0
	s_add_i32 s68, s1, s0
	s_mov_b64 s[40:41], 0
	v_mov_b32_e32 v203, 0x1010101
	v_lshlrev_b32_e32 v156, 2, v4
	v_lshlrev_b32_e32 v158, 2, v6
	v_mov_b32_e32 v204, 0x1010101
	v_mov_b32_e32 v205, 0x1010101
	v_mov_b32_e32 v206, 0x1010101
	v_mov_b32_e32 v207, 0x1010101
	v_mov_b32_e32 v208, 0x1010101
	v_mov_b32_e32 v209, 0x1010101
	v_mov_b32_e32 v210, 0x1010101
	v_mov_b32_e32 v211, 0x1010101
	v_mov_b32_e32 v212, 0x1010101
	v_mov_b32_e32 v213, 0x1010101
	v_mov_b32_e32 v214, 0x1010101
	v_mov_b32_e32 v215, 0x1010101
	v_mov_b32_e32 v216, 0x1010101
	v_mov_b32_e32 v217, 0x1010101
	v_mov_b32_e32 v218, 0x1010101
	v_mov_b32_e32 v199, 0x1010101
	v_mov_b32_e32 v200, 0x1010101
	v_mov_b32_e32 v201, 0x1010101
	v_mov_b32_e32 v202, 0x1010101
	v_mov_b32_e32 v195, 0x1010101
	v_mov_b32_e32 v196, 0x1010101
	v_mov_b32_e32 v197, 0x1010101
	v_mov_b32_e32 v198, 0x1010101
	v_mov_b32_e32 v191, 0x1010101
	v_mov_b32_e32 v192, 0x1010101
	v_mov_b32_e32 v193, 0x1010101
	v_mov_b32_e32 v194, 0x1010101
	v_mov_b32_e32 v187, 0x1010101
	v_mov_b32_e32 v188, 0x1010101
	v_mov_b32_e32 v189, 0x1010101
	v_mov_b32_e32 v190, 0x1010101
	v_readlane_b32 s5, v229, 46
	v_readlane_b32 s6, v229, 47
	v_readlane_b32 s7, v229, 48
	v_readlane_b32 s8, v229, 49
	v_readlane_b32 s9, v229, 50
	v_readlane_b32 s11, v229, 52
	v_readfirstlane_b32 s101, v160
	s_branch .LBB0_235

; #define LAS __attribute__((address_space(3)))
; DI void gload_lds16(const void* g, LAS char* l) { __builtin_amdgcn_global_load_lds((const unsigned*)g, (LAS unsigned*)l, 16, 0, 0); }
; template <bool WIDE = false>
; DI void gemm_core(f32x4 (&acc)[4][4], const GOp& g, LAS char* lds, const int tidx, const bool have_first, const bool has_next, const GOp& gn, const bool fw16 = false) {
;     ...
;     const int nk = g.K >> 6;
;     const int fr = lane & 15, fq = lane >> 4;
;     const int sw = (fq ^ (fr >> 1)) << 4;
;     const int aoff = (wm * 64 + fr) * 128, boff = 16384 + (wn * 64 + fr) * 128;
;     if (!have_first) gemm_issue(g, 0, lds, w, lane);
;     for (int kt = 0; kt < nk; ++kt) {
;         if (kt == 0 && have_first && fw16) {
;             asm volatile("s_waitcnt vmcnt(8) lgkmcnt(0)" ::: "memory");
;             __builtin_amdgcn_s_barrier();
;             asm volatile("" ::: "memory");
;         } else {
;             asm volatile("s_waitcnt vmcnt(0)" ::: "memory");
;             __syncthreads();
;         }
;         if (kt + 1 < nk) {
;             LAS char* base = lds + ((kt + 1) & 1) * 32768 + w * 1024;
;             const int kn = ((kt + 1 + g.krot) & (nk - 1)) * 64;
;             const bf16_t* Ak = g.A + kn; const bf16_t* Bk = g.Bt + kn;
; #pragma unroll
;             for (int j = 0; j < 4; ++j) { gload_lds16(Ak + oa[j], base + j * 4096); gload_lds16(Bk + ob[j], base + 16384 + j * 4096); }
;         } else if (has_next) gemm_issue(gn, 0, lds, w, lane);
.LBB0_257:
	v_mul_lo_u32 v2, s71, v161
	v_mul_lo_u32 v3, s34, v161
	v_mul_lo_u32 v84, s71, v179
	v_mul_lo_u32 v85, s34, v179
	v_mul_lo_u32 v87, s71, v180
	v_mul_lo_u32 v89, s34, v180
	v_mul_lo_u32 v91, s71, v181
	v_mul_lo_u32 v93, s34, v181
	s_lshr_b32 s34, s34, 6
	s_xor_b64 s[4:5], s[40:41], -1
	s_add_i32 s59, s34, -1
	s_andn2_b64 vcc, exec, s[4:5]
	v_add_u32_e32 v1, 0x4000, v160
	v_add_u32_e32 v114, 0x1000, v160
	v_add_u32_e32 v115, 0x5000, v160
	v_add_u32_e32 v116, 0x2000, v160
	v_add_u32_e32 v117, 0x6000, v160
	v_add_u32_e32 v118, 0x3000, v160
	v_or_b32_e32 v148, v2, v178
	v_or_b32_e32 v2, v3, v178
	v_or_b32_e32 v84, v84, v178
	v_or_b32_e32 v86, v85, v178
	v_or_b32_e32 v88, v87, v178
	v_or_b32_e32 v90, v89, v178
	v_or_b32_e32 v92, v91, v178
	v_or_b32_e32 v94, v93, v178
	s_cbranch_vccnz .LBB0_259
	v_mov_b32_e32 v3, v149
	v_mov_b32_e32 v85, v149
	v_mov_b32_e32 v87, v149
	v_mov_b32_e32 v89, v149
	v_mov_b32_e32 v91, v149
	v_mov_b32_e32 v93, v149
	v_mov_b32_e32 v95, v149
	s_and_b32 s8, s59, s0
	s_lshl_b32 s8, s8, 7
	s_add_u32 s4, s42, s8
	s_addc_u32 s5, s43, 0
	s_add_u32 s6, s44, s8
	s_addc_u32 s7, s45, 0
	v_lshl_add_u64 v[112:113], v[148:149], 1, s[4:5]
	s_add_u32 m0, s101, 0x0
	s_nop 0
	global_load_lds_dwordx4 v[112:113], off
	v_lshl_add_u64 v[112:113], v[2:3], 1, s[6:7]
	s_add_u32 m0, s101, 0x4000
	s_nop 0
	global_load_lds_dwordx4 v[112:113], off
	v_lshl_add_u64 v[112:113], v[84:85], 1, s[4:5]
	s_add_u32 m0, s101, 0x1000
	s_nop 0
	global_load_lds_dwordx4 v[112:113], off
	v_lshl_add_u64 v[112:113], v[86:87], 1, s[6:7]
	s_add_u32 m0, s101, 0x5000
	s_nop 0
	global_load_lds_dwordx4 v[112:113], off
	v_lshl_add_u64 v[112:113], v[88:89], 1, s[4:5]
	s_add_u32 m0, s101, 0x2000
	s_nop 0
	global_load_lds_dwordx4 v[112:113], off
	v_lshl_add_u64 v[112:113], v[90:91], 1, s[6:7]
	s_add_u32 m0, s101, 0x6000
	s_nop 0
	global_load_lds_dwordx4 v[112:113], off
	v_lshl_add_u64 v[112:113], v[92:93], 1, s[4:5]
	s_add_u32 m0, s101, 0x3000
	s_nop 0
	global_load_lds_dwordx4 v[112:113], off
	v_lshl_add_u64 v[112:113], v[94:95], 1, s[6:7]
	s_add_u32 m0, s101, 0x7000
	s_nop 0
	global_load_lds_dwordx4 v[112:113], off
	s_add_i32 s8, s0, 1
	s_and_b32 s8, s8, s59
	s_lshl_b32 s8, s8, 7
	s_add_u32 s4, s42, s8
	s_addc_u32 s5, s43, 0
	s_add_u32 s6, s44, s8
	s_addc_u32 s7, s45, 0
	v_lshl_add_u64 v[112:113], v[148:149], 1, s[4:5]
	s_add_u32 m0, s101, 0x8000
	s_nop 0
	global_load_lds_dwordx4 v[112:113], off
	v_lshl_add_u64 v[112:113], v[2:3], 1, s[6:7]
	s_add_u32 m0, s101, 0xc000
	s_nop 0
	global_load_lds_dwordx4 v[112:113], off
	v_lshl_add_u64 v[112:113], v[84:85], 1, s[4:5]
	s_add_u32 m0, s101, 0x9000
	s_nop 0
	global_load_lds_dwordx4 v[112:113], off
	v_lshl_add_u64 v[112:113], v[86:87], 1, s[6:7]
	s_add_u32 m0, s101, 0xd000
	s_nop 0
	global_load_lds_dwordx4 v[112:113], off
	v_lshl_add_u64 v[112:113], v[88:89], 1, s[4:5]
	s_add_u32 m0, s101, 0xa000
	s_nop 0
	global_load_lds_dwordx4 v[112:113], off
	v_lshl_add_u64 v[112:113], v[90:91], 1, s[6:7]
	s_add_u32 m0, s101, 0xe000
	s_nop 0
	global_load_lds_dwordx4 v[112:113], off
	v_lshl_add_u64 v[112:113], v[92:93], 1, s[4:5]
	s_add_u32 m0, s101, 0xb000
	s_nop 0
	global_load_lds_dwordx4 v[112:113], off
	v_lshl_add_u64 v[112:113], v[94:95], 1, s[6:7]
	s_add_u32 m0, s101, 0xf000
	s_nop 0
	global_load_lds_dwordx4 v[112:113], off
.LBB0_259:
	s_lshr_b32 s4, s33, 6
	s_add_i32 s4, s4, -1
	s_mov_b32 s100, s4
	s_and_b32 s4, s4, s72
	s_lshl_b32 s6, s4, 7
	s_add_u32 s4, s54, s6
	s_addc_u32 s5, s55, 0
	v_mul_lo_u32 v96, s70, v161
	s_add_u32 s6, s56, s6
	v_mul_lo_u32 v98, s33, v161
	v_mul_lo_u32 v100, s70, v179
	v_mul_lo_u32 v102, s33, v179
	v_mul_lo_u32 v104, s70, v180
	v_mul_lo_u32 v106, s33, v180
	v_mul_lo_u32 v108, s70, v181
	v_mul_lo_u32 v110, s33, v181
	v_or_b32_e32 v96, v96, v178
	v_mov_b32_e32 v97, v149
	s_addc_u32 s7, s57, 0
	v_or_b32_e32 v98, v98, v178
	v_mov_b32_e32 v99, v149
	v_or_b32_e32 v100, v100, v178
	v_mov_b32_e32 v101, v149
	v_or_b32_e32 v102, v102, v178
	v_mov_b32_e32 v103, v149
	v_or_b32_e32 v104, v104, v178
	v_mov_b32_e32 v105, v149
	v_or_b32_e32 v106, v106, v178
	v_mov_b32_e32 v107, v149
	v_or_b32_e32 v108, v108, v178
	v_mov_b32_e32 v109, v149
	v_or_b32_e32 v110, v110, v178
	v_mov_b32_e32 v111, v149
	s_mov_b64 s[40:41], s[50:51]
	v_mov_b32_e32 v3, v149
	v_mov_b32_e32 v85, v149
	v_mov_b32_e32 v87, v149
	v_mov_b32_e32 v89, v149
	v_mov_b32_e32 v91, v149
	v_mov_b32_e32 v93, v149
	v_mov_b32_e32 v95, v149
	v_lshl_add_u64 v[96:97], v[96:97], 1, s[4:5]
	v_lshl_add_u64 v[98:99], v[98:99], 1, s[6:7]
	v_lshl_add_u64 v[100:101], v[100:101], 1, s[4:5]
	v_lshl_add_u64 v[102:103], v[102:103], 1, s[6:7]
	v_lshl_add_u64 v[104:105], v[104:105], 1, s[4:5]
	v_lshl_add_u64 v[106:107], v[106:107], 1, s[6:7]
	v_lshl_add_u64 v[108:109], v[108:109], 1, s[4:5]
	v_lshl_add_u64 v[110:111], v[110:111], 1, s[6:7]
	s_add_i32 s0, s0, 1
	s_mov_b32 s33, 0
	s_mov_b32 s4, 0
	s_movk_i32 s57, 0xeff0
.LBB0_260:
	s_mov_b32 s8, 0
.Lmg_top:
	s_add_i32 s56, s8, 1
	s_cmp_lt_u32 s56, s34
	s_cselect_b64 s[52:53], -1, 0
	s_or_b64 s[52:53], s[52:53], s[50:51]
	s_and_b64 vcc, exec, s[52:53]
	s_cbranch_vccz .Lmg_w0
	s_waitcnt vmcnt(8) lgkmcnt(0)
	s_branch .Lmg_wd
.Lmg_w0:
	s_waitcnt vmcnt(0) lgkmcnt(0)
; #define LAS __attribute__((address_space(3)))
; DI void gload_lds16(const void* g, LAS char* l) { __builtin_amdgcn_global_load_lds((const unsigned*)g, (LAS unsigned*)l, 16, 0, 0); }
; template <bool WIDE = false>
; DI void gemm_core(f32x4 (&acc)[4][4], const GOp& g, LAS char* lds, const int tidx, const bool have_first, const bool has_next, const GOp& gn, const bool fw16 = false) {
;     ...
;         if (kt + 1 < nk) {
;             LAS char* base = lds + ((kt + 1) & 1) * 32768 + w * 1024;
;             const int kn = ((kt + 1 + g.krot) & (nk - 1)) * 64;
;             const bf16_t* Ak = g.A + kn; const bf16_t* Bk = g.Bt + kn;
; #pragma unroll
;             for (int j = 0; j < 4; ++j) { gload_lds16(Ak + oa[j], base + j * 4096); gload_lds16(Bk + ob[j], base + 16384 + j * 4096); }
;         } else if (has_next) gemm_issue(gn, 0, lds, w, lane);
;         LAS char* st = lds + (kt & 1) * 32768;
;         if constexpr (WIDE) {
;         bf16x8 af[2][4], bfr[2][4];
; #pragma unroll
;         for (int ks = 0; ks < 2; ++ks) {
; #pragma unroll
;             for (int i = 0; i < 4; ++i) af[ks][i] = *(LAS bf16x8*)(st + aoff + i * 2048 + (sw ^ (ks * 64)));
; #pragma unroll
;             for (int i = 0; i < 4; ++i) bfr[ks][i] = *(LAS bf16x8*)(st + boff + i * 2048 + (sw ^ (ks * 64)));
;         }
;         __builtin_amdgcn_sched_barrier(0);
;         __builtin_amdgcn_s_setprio(1);
; #pragma unroll
;         for (int ks = 0; ks < 2; ++ks)
; #pragma unroll
;             for (int mi = 0; mi < 4; ++mi)
; #pragma unroll
;                 for (int ni = 0; ni < 4; ++ni) acc[mi][ni] = __builtin_amdgcn_mfma_f32_16x16x32_bf16(bfr[ks][ni], af[ks][mi], acc[mi][ni], 0, 0, 0);
;         __builtin_amdgcn_s_setprio(0);
;         } else {
; #pragma unroll
;         for (int ks = 0; ks < 2; ++ks) {
;             bf16x8 af[4], bfr[4];
; #pragma unroll
;             for (int i = 0; i < 4; ++i) af[i] = *(LAS bf16x8*)(st + aoff + i * 2048 + (sw ^ (ks * 64)));
; #pragma unroll
;             for (int i = 0; i < 4; ++i) bfr[i] = *(LAS bf16x8*)(st + boff + i * 2048 + (sw ^ (ks * 64)));
;             __builtin_amdgcn_s_setprio(1);
; #pragma unroll
;             for (int mi = 0; mi < 4; ++mi)
; #pragma unroll
;                 for (int ni = 0; ni < 4; ++ni) acc[mi][ni] = __builtin_amdgcn_mfma_f32_16x16x32_bf16(bfr[ni], af[mi], acc[mi][ni], 0, 0, 0);
;             __builtin_amdgcn_s_setprio(0);
;         }
.Lmg_wd:
	s_barrier
	s_lshl_b32 s33, s8, 15
	s_and_b32 s33, s33, 0x8000
	v_add_u32_e32 v112, s33, v184
	v_or_b32_e32 v113, s33, v185
	v_add_u32_e32 v119, v112, v182
	ds_read_b128 v[120:123], v119 offset:0
	ds_read_b128 v[124:127], v119 offset:2048
	ds_read_b128 v[128:131], v119 offset:4096
	ds_read_b128 v[132:135], v119 offset:6144
	v_add_u32_e32 v119, v113, v182
	ds_read_b128 v[136:139], v119 offset:16384
	ds_read_b128 v[140:143], v119 offset:18432
	ds_read_b128 v[144:147], v119 offset:20480
	ds_read_b128 v[220:223], v119 offset:22528
	s_setprio 1
	s_waitcnt lgkmcnt(0)
	v_mfma_f32_16x16x32_bf16 v[80:83], v[136:139], v[120:123], v[80:83]
	v_mfma_f32_16x16x32_bf16 v[76:79], v[140:143], v[120:123], v[76:79]
	v_mfma_f32_16x16x32_bf16 v[72:75], v[144:147], v[120:123], v[72:75]
	v_mfma_f32_16x16x32_bf16 v[68:71], v[220:223], v[120:123], v[68:71]
	v_mfma_f32_16x16x32_bf16 v[64:67], v[136:139], v[124:127], v[64:67]
	v_mfma_f32_16x16x32_bf16 v[60:63], v[140:143], v[124:127], v[60:63]
	v_mfma_f32_16x16x32_bf16 v[56:59], v[144:147], v[124:127], v[56:59]
	v_mfma_f32_16x16x32_bf16 v[52:55], v[220:223], v[124:127], v[52:55]
	v_mfma_f32_16x16x32_bf16 v[48:51], v[136:139], v[128:131], v[48:51]
	v_mfma_f32_16x16x32_bf16 v[44:47], v[140:143], v[128:131], v[44:47]
	v_mfma_f32_16x16x32_bf16 v[40:43], v[144:147], v[128:131], v[40:43]
	v_mfma_f32_16x16x32_bf16 v[36:39], v[220:223], v[128:131], v[36:39]
	v_mfma_f32_16x16x32_bf16 v[32:35], v[136:139], v[132:135], v[32:35]
	v_mfma_f32_16x16x32_bf16 v[28:31], v[140:143], v[132:135], v[28:31]
	v_mfma_f32_16x16x32_bf16 v[8:11], v[144:147], v[132:135], v[8:11]
	v_mfma_f32_16x16x32_bf16 v[4:7], v[220:223], v[132:135], v[4:7]
	s_setprio 0
	v_add_u32_e32 v119, v112, v186
	ds_read_b128 v[120:123], v119 offset:0
	ds_read_b128 v[124:127], v119 offset:2048
	ds_read_b128 v[128:131], v119 offset:4096
	ds_read_b128 v[132:135], v119 offset:6144
	v_add_u32_e32 v112, v113, v186
	ds_read_b128 v[136:139], v112 offset:16384
	ds_read_b128 v[140:143], v112 offset:18432
	ds_read_b128 v[144:147], v112 offset:20480
	ds_read_b128 v[220:223], v112 offset:22528
	s_waitcnt lgkmcnt(0)
	s_barrier
	s_add_u32 s5, s101, s33
	s_add_i32 s6, s8, 2
	s_cmp_lt_u32 s6, s34
	s_cbranch_scc0 .Lmg_next
	s_add_i32 s6, s8, s0
	s_add_i32 s6, s6, 1
	s_and_b32 s6, s6, s59
	s_lshl_b32 s4, s6, 7
	s_add_u32 s52, s42, s4
	s_addc_u32 s53, s43, 0
	s_add_u32 s54, s44, s4
	s_addc_u32 s55, s45, 0
	v_lshl_add_u64 v[112:113], v[148:149], 1, s[52:53]
	s_add_u32 m0, s5, 0x0
	s_nop 0
	global_load_lds_dwordx4 v[112:113], off
	v_lshl_add_u64 v[112:113], v[2:3], 1, s[54:55]
	s_add_u32 m0, s5, 0x4000
	s_nop 0
	global_load_lds_dwordx4 v[112:113], off
	v_lshl_add_u64 v[112:113], v[84:85], 1, s[52:53]
	s_add_u32 m0, s5, 0x1000
	s_nop 0
	global_load_lds_dwordx4 v[112:113], off
	v_lshl_add_u64 v[112:113], v[86:87], 1, s[54:55]
	s_add_u32 m0, s5, 0x5000
	s_nop 0
	global_load_lds_dwordx4 v[112:113], off
	v_lshl_add_u64 v[112:113], v[88:89], 1, s[52:53]
	s_add_u32 m0, s5, 0x2000
	s_nop 0
	global_load_lds_dwordx4 v[112:113], off
	v_lshl_add_u64 v[112:113], v[90:91], 1, s[54:55]
	s_add_u32 m0, s5, 0x6000
	s_nop 0
	global_load_lds_dwordx4 v[112:113], off
	v_lshl_add_u64 v[112:113], v[92:93], 1, s[52:53]
	s_add_u32 m0, s5, 0x3000
	s_nop 0
	global_load_lds_dwordx4 v[112:113], off
	v_lshl_add_u64 v[112:113], v[94:95], 1, s[54:55]
	s_add_u32 m0, s5, 0x7000
	s_nop 0
	global_load_lds_dwordx4 v[112:113], off
	s_branch .Lmg_issued
.Lmg_next:
	s_and_b64 vcc, exec, s[50:51]
	s_cbranch_vccz .Lmg_issued
	s_sub_i32 s6, s6, s34
	s_and_b32 s4, s72, s100
	s_add_i32 s7, s72, s6
	s_and_b32 s7, s7, s100
	s_sub_i32 s52, s7, s4
	s_lshl_b32 s52, s52, 7
	s_ashr_i32 s53, s52, 31
	v_lshl_add_u64 v[112:113], v[96:97], 0, s[52:53]
	s_add_u32 m0, s5, 0x0
	s_nop 0
	global_load_lds_dwordx4 v[112:113], off
	v_lshl_add_u64 v[112:113], v[98:99], 0, s[52:53]
	s_add_u32 m0, s5, 0x4000
	s_nop 0
	global_load_lds_dwordx4 v[112:113], off
	v_lshl_add_u64 v[112:113], v[100:101], 0, s[52:53]
	s_add_u32 m0, s5, 0x1000
	s_nop 0
	global_load_lds_dwordx4 v[112:113], off
	v_lshl_add_u64 v[112:113], v[102:103], 0, s[52:53]
	s_add_u32 m0, s5, 0x5000
	s_nop 0
	global_load_lds_dwordx4 v[112:113], off
	v_lshl_add_u64 v[112:113], v[104:105], 0, s[52:53]
	s_add_u32 m0, s5, 0x2000
	s_nop 0
	global_load_lds_dwordx4 v[112:113], off
	v_lshl_add_u64 v[112:113], v[106:107], 0, s[52:53]
	s_add_u32 m0, s5, 0x6000
	s_nop 0
	global_load_lds_dwordx4 v[112:113], off
	v_lshl_add_u64 v[112:113], v[108:109], 0, s[52:53]
	s_add_u32 m0, s5, 0x3000
	s_nop 0
	global_load_lds_dwordx4 v[112:113], off
	v_lshl_add_u64 v[112:113], v[110:111], 0, s[52:53]
	s_add_u32 m0, s5, 0x7000
	s_nop 0
	global_load_lds_dwordx4 v[112:113], off
.Lmg_issued:
	s_setprio 1
	v_mfma_f32_16x16x32_bf16 v[80:83], v[136:139], v[120:123], v[80:83]
	v_mfma_f32_16x16x32_bf16 v[76:79], v[140:143], v[120:123], v[76:79]
	v_mfma_f32_16x16x32_bf16 v[72:75], v[144:147], v[120:123], v[72:75]
	v_mfma_f32_16x16x32_bf16 v[68:71], v[220:223], v[120:123], v[68:71]
	v_mfma_f32_16x16x32_bf16 v[64:67], v[136:139], v[124:127], v[64:67]
	v_mfma_f32_16x16x32_bf16 v[60:63], v[140:143], v[124:127], v[60:63]
	v_mfma_f32_16x16x32_bf16 v[56:59], v[144:147], v[124:127], v[56:59]
	v_mfma_f32_16x16x32_bf16 v[52:55], v[220:223], v[124:127], v[52:55]
	v_mfma_f32_16x16x32_bf16 v[48:51], v[136:139], v[128:131], v[48:51]
	v_mfma_f32_16x16x32_bf16 v[44:47], v[140:143], v[128:131], v[44:47]
	v_mfma_f32_16x16x32_bf16 v[40:43], v[144:147], v[128:131], v[40:43]
	v_mfma_f32_16x16x32_bf16 v[36:39], v[220:223], v[128:131], v[36:39]
	v_mfma_f32_16x16x32_bf16 v[32:35], v[136:139], v[132:135], v[32:35]
	v_mfma_f32_16x16x32_bf16 v[28:31], v[140:143], v[132:135], v[28:31]
	v_mfma_f32_16x16x32_bf16 v[8:11], v[144:147], v[132:135], v[8:11]
	v_mfma_f32_16x16x32_bf16 v[4:7], v[220:223], v[132:135], v[4:7]
	s_setprio 0
	s_add_i32 s8, s8, 1
	s_cmp_lt_u32 s8, s34
	s_cbranch_scc1 .Lmg_top
